# norm phases 7 and 14 wave_sum: xor 1,2,4,8 butterfly steps by DPP adds instead of ds_bpermute round trips (on top of gla_out DPP)
# baseline (speedup 1.0000x reference)
; __device__ __forceinline__ f32x4 ld4_bf16(const bf16_t* p) { const u32x2 w = *(const u32x2*)p; return (f32x4){__uint_as_float(w.x << 16), __uint_as_float(w.x & 0xffff0000u), __uint_as_float(w.y << 16), __uint_as_float(w.y & 0xffff0000u)}; }
; __device__ __forceinline__ float wave_sum(float v) {
; #pragma unroll
;     for (int o = 1; o < 64; o <<= 1) v += __shfl_xor(v, o);
;     return v;
; __device__ __forceinline__ void norm_phase(const float* src_lat, const float* src_ctx, int nrows, const float* gain, const float* mod_l, int sh_chunk, int sc_chunk, bf16_t* dst, const bf16_t* lr_t = nullptr, bf16_t* lr_out = nullptr, const bf16_t* src16 = nullptr, LAS unsigned char* lds = nullptr) {
;     ...
;         f32x4 v[8]; float ss = 0.f;
; #pragma unroll
;         for (int j = 0; j < 8; ++j) { v[j] = src16 ? ld4_bf16(src16 + (size_t)row * D + (lane + 64 * j) * 4) : *(const f32x4*)(xr + (lane + 64 * j) * 4); ss += (v[j][0] * v[j][0] + v[j][1] * v[j][1]) + (v[j][2] * v[j][2] + v[j][3] * v[j][3]); }
;         const float rstd = rsqrtf(wave_sum(ss) * (1.f / D) + 1e-6f);
.LBB0_766:
	s_or_b64 exec, exec, s[10:11]
	v_ashrrev_i32_e32 v95, 31, v94
	v_lshlrev_b64 v[94:95], 12, v[94:95]
	v_lshl_add_u64 v[102:103], v[76:77], 0, v[94:95]
	global_load_dwordx2 v[104:105], v[102:103], off
	global_load_dwordx2 v[106:107], v[102:103], off offset:512
	global_load_dwordx2 v[108:109], v[102:103], off offset:1024
	global_load_dwordx2 v[110:111], v[102:103], off offset:1536
	global_load_dwordx2 v[112:113], v[102:103], off offset:2048
	global_load_dwordx2 v[114:115], v[102:103], off offset:2560
	global_load_dwordx2 v[116:117], v[102:103], off offset:3072
	global_load_dwordx2 v[118:119], v[102:103], off offset:3584
	v_and_b32_e32 v83, 64, v100
	v_add_u32_e32 v83, 64, v83
	v_lshl_add_u64 v[94:95], v[78:79], 0, v[94:95]
	s_waitcnt vmcnt(7)
	v_lshlrev_b32_e32 v102, 16, v104
	v_and_b32_e32 v103, 0xffff0000, v104
	v_lshlrev_b32_e32 v104, 16, v105
	v_and_b32_e32 v105, 0xffff0000, v105
	s_waitcnt vmcnt(6)
	v_lshlrev_b32_e32 v121, 16, v107
	v_lshlrev_b32_e32 v120, 16, v106
	v_and_b32_e32 v107, 0xffff0000, v107
	v_and_b32_e32 v106, 0xffff0000, v106
	s_waitcnt vmcnt(4)
	v_lshlrev_b32_e32 v125, 16, v110
	v_and_b32_e32 v127, 0xffff0000, v110
	s_waitcnt vmcnt(1)
	v_and_b32_e32 v133, 0xffff0000, v116
	v_mul_f32_e32 v124, v105, v105
	v_mul_f32_e32 v126, v103, v103
	v_lshlrev_b32_e32 v122, 16, v108
	v_and_b32_e32 v123, 0xffff0000, v108
	v_lshlrev_b32_e32 v108, 16, v109
	v_and_b32_e32 v109, 0xffff0000, v109
	v_lshlrev_b32_e32 v132, 16, v116
	v_pk_mul_f32 v[138:139], v[106:107], v[106:107]
	v_mov_b32_e32 v141, v125
	v_mul_f32_e32 v140, v133, v133
	v_pk_fma_f32 v[148:149], v[104:105], v[104:105], v[124:125] op_sel_hi:[1,1,0]
	v_pk_fma_f32 v[150:151], v[102:103], v[102:103], v[126:127] op_sel_hi:[1,1,0]
	v_lshlrev_b32_e32 v110, 16, v111
	v_and_b32_e32 v111, 0xffff0000, v111
	s_waitcnt vmcnt(0)
	v_lshlrev_b32_e32 v135, 16, v118
	v_and_b32_e32 v137, 0xffff0000, v118
	v_mul_f32_e32 v134, v123, v123
	v_mul_f32_e32 v136, v109, v109
	v_pk_fma_f32 v[138:139], v[120:121], v[120:121], v[138:139]
	v_pk_fma_f32 v[156:157], v[132:133], v[132:133], v[140:141] op_sel_hi:[1,1,0]
	v_mov_b32_e32 v124, v150
	v_mov_b32_e32 v140, v148
	v_mul_f32_e32 v85, v127, v127
	v_mul_f32_e32 v87, v110, v110
	v_mul_f32_e32 v89, v111, v111
	v_pk_fma_f32 v[152:153], v[122:123], v[122:123], v[134:135] op_sel_hi:[1,1,0]
	v_pk_fma_f32 v[154:155], v[108:109], v[108:109], v[136:137] op_sel_hi:[1,1,0]
	v_pk_add_f32 v[148:149], v[150:151], v[148:149]
	v_pk_add_f32 v[138:139], v[138:139], v[138:139] op_sel:[0,1] op_sel_hi:[1,0]
	v_pk_mul_f32 v[140:141], v[124:125], v[140:141]
	v_lshlrev_b32_e32 v129, 16, v113
	v_lshlrev_b32_e32 v128, 16, v112
	v_and_b32_e32 v113, 0xffff0000, v113
	v_and_b32_e32 v112, 0xffff0000, v112
	v_mov_b32_e32 v153, v87
	v_mov_b32_e32 v155, v89
	v_mov_b32_e32 v139, v85
	v_mov_b32_e32 v149, v141
	v_pk_mul_f32 v[142:143], v[112:113], v[112:113]
	v_pk_add_f32 v[150:151], v[152:153], v[154:155]
	v_pk_add_f32 v[138:139], v[148:149], v[138:139]
	v_lshlrev_b32_e32 v131, 16, v115
	v_lshlrev_b32_e32 v130, 16, v114
	v_and_b32_e32 v115, 0xffff0000, v115
	v_and_b32_e32 v114, 0xffff0000, v114
	v_lshlrev_b32_e32 v116, 16, v117
	v_and_b32_e32 v117, 0xffff0000, v117
	v_pk_fma_f32 v[142:143], v[128:129], v[128:129], v[142:143]
	v_pk_add_f32 v[138:139], v[138:139], v[150:151]
	v_pk_mul_f32 v[144:145], v[114:115], v[114:115]
	v_mov_b32_e32 v147, v135
	v_mul_f32_e32 v146, v117, v117
	v_pk_add_f32 v[142:143], v[142:143], v[142:143] op_sel:[0,1] op_sel_hi:[1,0]
	v_pk_add_f32 v[138:139], v[138:139], v[138:139] op_sel:[0,1] op_sel_hi:[1,0]
	v_lshlrev_b32_e32 v118, 16, v119
	v_and_b32_e32 v119, 0xffff0000, v119
	v_pk_fma_f32 v[144:145], v[130:131], v[130:131], v[144:145]
	v_pk_fma_f32 v[158:159], v[116:117], v[116:117], v[146:147] op_sel_hi:[1,1,0]
	v_mov_b32_e32 v146, v142
	v_mov_b32_e32 v134, v138
	v_mul_f32_e32 v91, v137, v137
	v_mul_f32_e32 v93, v118, v118
	v_mul_f32_e32 v101, v119, v119
	v_pk_add_f32 v[144:145], v[144:145], v[144:145] op_sel:[0,1] op_sel_hi:[1,0]
	v_pk_add_f32 v[138:139], v[138:139], v[142:143]
	v_pk_mul_f32 v[140:141], v[134:135], v[146:147]
	v_mov_b32_e32 v157, v93
	v_mov_b32_e32 v159, v101
	v_mov_b32_e32 v145, v91
	v_mov_b32_e32 v139, v141
	v_xor_b32_e32 v87, 1, v100
	v_pk_add_f32 v[152:153], v[156:157], v[158:159]
	v_pk_add_f32 v[138:139], v[138:139], v[144:145]
	v_cmp_lt_i32_e32 vcc, v87, v83
	v_pk_add_f32 v[138:139], v[138:139], v[152:153]
	v_mov_b32_e32 v126, v125
	v_cndmask_b32_e32 v87, v100, v87, vcc
	v_add_f32_e32 v85, v138, v139
	v_lshlrev_b32_e32 v87, 2, v87
	v_mov_b32_e32 v136, v135
	s_nop 0
	v_add_f32_dpp v85, v85, v85 quad_perm:[1,0,3,2] row_mask:0xf bank_mask:0xf
	s_nop 1
	v_add_f32_dpp v85, v85, v85 quad_perm:[2,3,0,1] row_mask:0xf bank_mask:0xf
	s_nop 1
	v_add_f32_dpp v85, v85, v85 row_half_mirror row_mask:0xf bank_mask:0xf
	s_nop 1
	v_add_f32_dpp v85, v85, v85 row_mirror row_mask:0xf bank_mask:0xf
	v_xor_b32_e32 v87, 16, v100
	v_cmp_lt_i32_e32 vcc, v87, v83
	s_nop 1
	v_cndmask_b32_e32 v87, v100, v87, vcc
	v_lshlrev_b32_e32 v87, 2, v87
	ds_bpermute_b32 v87, v87, v85
	s_waitcnt lgkmcnt(0)
; __device__ __forceinline__ unsigned cvt_pk_bf16(float lo, float hi) { const f32x2 v = {lo, hi}; const bf16v2_t b = __builtin_convertvector(v, bf16v2_t); return __builtin_bit_cast(unsigned, b); }
; __device__ __forceinline__ void norm_phase(const float* src_lat, const float* src_ctx, int nrows, const float* gain, const float* mod_l, int sh_chunk, int sc_chunk, bf16_t* dst, const bf16_t* lr_t = nullptr, bf16_t* lr_out = nullptr, const bf16_t* src16 = nullptr, LAS unsigned char* lds = nullptr) {
;     ...
;         const float rstd = rsqrtf(wave_sum(ss) * (1.f / D) + 1e-6f);
; #pragma unroll
;         for (int j = 0; j < 8; ++j) { const int c0 = (lane + 64 * j) * 4;
;             const f32x4 y = v[j] * rstd * gam[j] + shv[j];
;             u32x2 w; w.x = cvt_pk_bf16(y[0], y[1]); w.y = cvt_pk_bf16(y[2], y[3]);
;             *(u32x2*)(dst + (size_t)row * D + c0) = w; v[j] = y; }
	v_add_f32_e32 v85, v85, v87
	v_xor_b32_e32 v87, 32, v100
	v_cmp_lt_i32_e32 vcc, v87, v83
	s_nop 1
	v_cndmask_b32_e32 v83, v100, v87, vcc
	v_lshlrev_b32_e32 v83, 2, v83
	ds_bpermute_b32 v83, v83, v85
	s_waitcnt lgkmcnt(0)
	v_add_f32_e32 v83, v85, v83
	v_fmamk_f32 v83, v83, 0x3a000000, v99
	v_mul_f32_e32 v85, 0x4b800000, v83
	v_cmp_gt_f32_e32 vcc, s16, v83
	s_nop 1
	v_cndmask_b32_e32 v83, v83, v85, vcc
	v_rsq_f32_e32 v83, v83
	s_nop 0
	v_mul_f32_e32 v85, 0x45800000, v83
	v_cndmask_b32_e32 v124, v83, v85, vcc
	v_pk_mul_f32 v[102:103], v[124:125], v[102:103] op_sel_hi:[0,1]
	v_pk_mul_f32 v[104:105], v[124:125], v[104:105] op_sel_hi:[0,1]
	v_pk_fma_f32 v[104:105], v[34:35], v[104:105], v[2:3]
	v_pk_fma_f32 v[102:103], v[32:33], v[102:103], v[0:1]
	s_nop 0
	v_cvt_pk_bf16_f32 v102, v102, v103
	v_cvt_pk_bf16_f32 v103, v104, v105
	global_store_dwordx2 v[94:95], v[102:103], off
	v_mov_b32_e32 v102, v120
	v_mov_b32_e32 v103, v106
	v_mov_b32_e32 v106, v121
	v_pk_mul_f32 v[102:103], v[124:125], v[102:103] op_sel_hi:[0,1]
	v_pk_mul_f32 v[104:105], v[124:125], v[106:107] op_sel_hi:[0,1]
	v_pk_fma_f32 v[104:105], v[38:39], v[104:105], v[6:7]
	v_pk_fma_f32 v[102:103], v[36:37], v[102:103], v[4:5]
	s_nop 0
	v_cvt_pk_bf16_f32 v102, v102, v103
	v_cvt_pk_bf16_f32 v103, v104, v105
	global_store_dwordx2 v[94:95], v[102:103], off offset:512
	v_pk_mul_f32 v[102:103], v[124:125], v[122:123] op_sel_hi:[0,1]
	v_pk_mul_f32 v[104:105], v[124:125], v[108:109] op_sel_hi:[0,1]
	v_pk_fma_f32 v[104:105], v[42:43], v[104:105], v[10:11]
	v_pk_fma_f32 v[102:103], v[40:41], v[102:103], v[8:9]
	s_nop 0
	v_cvt_pk_bf16_f32 v102, v102, v103
	v_cvt_pk_bf16_f32 v103, v104, v105
	global_store_dwordx2 v[94:95], v[102:103], off offset:1024
	v_pk_mul_f32 v[102:103], v[124:125], v[126:127] op_sel_hi:[0,1]
	v_pk_mul_f32 v[104:105], v[124:125], v[110:111] op_sel_hi:[0,1]
	v_pk_fma_f32 v[104:105], v[46:47], v[104:105], v[14:15]
	v_pk_fma_f32 v[102:103], v[44:45], v[102:103], v[12:13]
	s_nop 0
	v_cvt_pk_bf16_f32 v102, v102, v103
	v_cvt_pk_bf16_f32 v103, v104, v105
	global_store_dwordx2 v[94:95], v[102:103], off offset:1536
	v_mov_b32_e32 v102, v128
	v_mov_b32_e32 v103, v112
	v_mov_b32_e32 v112, v129
	v_pk_mul_f32 v[102:103], v[124:125], v[102:103] op_sel_hi:[0,1]
	v_pk_mul_f32 v[104:105], v[124:125], v[112:113] op_sel_hi:[0,1]
	v_pk_fma_f32 v[104:105], v[50:51], v[104:105], v[18:19]
	v_pk_fma_f32 v[102:103], v[48:49], v[102:103], v[16:17]
	s_nop 0
	v_cvt_pk_bf16_f32 v102, v102, v103
	v_cvt_pk_bf16_f32 v103, v104, v105
	global_store_dwordx2 v[94:95], v[102:103], off offset:2048
	v_mov_b32_e32 v102, v130
	v_mov_b32_e32 v103, v114
	v_mov_b32_e32 v114, v131
	v_pk_mul_f32 v[102:103], v[124:125], v[102:103] op_sel_hi:[0,1]
	v_pk_mul_f32 v[104:105], v[124:125], v[114:115] op_sel_hi:[0,1]
	v_pk_fma_f32 v[104:105], v[54:55], v[104:105], v[22:23]
	v_pk_fma_f32 v[102:103], v[52:53], v[102:103], v[20:21]
	s_nop 0
	v_cvt_pk_bf16_f32 v102, v102, v103
	v_cvt_pk_bf16_f32 v103, v104, v105
	global_store_dwordx2 v[94:95], v[102:103], off offset:2560
	v_pk_mul_f32 v[102:103], v[124:125], v[132:133] op_sel_hi:[0,1]
	v_pk_mul_f32 v[104:105], v[124:125], v[116:117] op_sel_hi:[0,1]
	v_pk_fma_f32 v[104:105], v[58:59], v[104:105], v[26:27]
	v_pk_fma_f32 v[102:103], v[56:57], v[102:103], v[24:25]
	s_nop 0
	v_cvt_pk_bf16_f32 v102, v102, v103
	v_cvt_pk_bf16_f32 v103, v104, v105
	global_store_dwordx2 v[94:95], v[102:103], off offset:3072
	v_pk_mul_f32 v[102:103], v[124:125], v[136:137] op_sel_hi:[0,1]
	v_pk_mul_f32 v[104:105], v[124:125], v[118:119] op_sel_hi:[0,1]
	v_pk_fma_f32 v[104:105], v[62:63], v[104:105], v[30:31]
	v_pk_fma_f32 v[102:103], v[60:61], v[102:103], v[28:29]
	s_nop 0
	v_cvt_pk_bf16_f32 v102, v102, v103
	v_cvt_pk_bf16_f32 v103, v104, v105
	global_store_dwordx2 v[94:95], v[102:103], off offset:3584

; __device__ __forceinline__ f32x4 ld4_bf16(const bf16_t* p) { const u32x2 w = *(const u32x2*)p; return (f32x4){__uint_as_float(w.x << 16), __uint_as_float(w.x & 0xffff0000u), __uint_as_float(w.y << 16), __uint_as_float(w.y & 0xffff0000u)}; }
; __device__ __forceinline__ float wave_sum(float v) {
; #pragma unroll
;     for (int o = 1; o < 64; o <<= 1) v += __shfl_xor(v, o);
;     return v;
; __device__ __forceinline__ void norm_phase(const float* src_lat, const float* src_ctx, int nrows, const float* gain, const float* mod_l, int sh_chunk, int sc_chunk, bf16_t* dst, const bf16_t* lr_t = nullptr, bf16_t* lr_out = nullptr, const bf16_t* src16 = nullptr, LAS unsigned char* lds = nullptr) {
;     ...
;         f32x4 v[8]; float ss = 0.f;
; #pragma unroll
;         for (int j = 0; j < 8; ++j) { v[j] = src16 ? ld4_bf16(src16 + (size_t)row * D + (lane + 64 * j) * 4) : *(const f32x4*)(xr + (lane + 64 * j) * 4); ss += (v[j][0] * v[j][0] + v[j][1] * v[j][1]) + (v[j][2] * v[j][2] + v[j][3] * v[j][3]); }
;         const float rstd = rsqrtf(wave_sum(ss) * (1.f / D) + 1e-6f);
.LBB0_1454:
	s_or_b64 exec, exec, s[10:11]
	v_ashrrev_i32_e32 v101, 31, v100
	v_lshlrev_b64 v[100:101], 12, v[100:101]
	v_lshl_add_u64 v[108:109], v[82:83], 0, v[100:101]
	global_load_dwordx2 v[110:111], v[108:109], off
	global_load_dwordx2 v[112:113], v[108:109], off offset:512
	global_load_dwordx2 v[114:115], v[108:109], off offset:1024
	global_load_dwordx2 v[116:117], v[108:109], off offset:1536
	global_load_dwordx2 v[118:119], v[108:109], off offset:2048
	global_load_dwordx2 v[120:121], v[108:109], off offset:2560
	global_load_dwordx2 v[122:123], v[108:109], off offset:3072
	global_load_dwordx2 v[124:125], v[108:109], off offset:3584
	v_and_b32_e32 v89, 64, v106
	v_add_u32_e32 v89, 64, v89
	v_lshl_add_u64 v[100:101], v[84:85], 0, v[100:101]
	s_waitcnt vmcnt(7)
	v_lshlrev_b32_e32 v108, 16, v110
	v_and_b32_e32 v109, 0xffff0000, v110
	v_lshlrev_b32_e32 v110, 16, v111
	v_and_b32_e32 v111, 0xffff0000, v111
	s_waitcnt vmcnt(6)
	v_lshlrev_b32_e32 v127, 16, v113
	v_lshlrev_b32_e32 v126, 16, v112
	v_and_b32_e32 v113, 0xffff0000, v113
	v_and_b32_e32 v112, 0xffff0000, v112
	s_waitcnt vmcnt(4)
	v_lshlrev_b32_e32 v131, 16, v116
	v_and_b32_e32 v133, 0xffff0000, v116
	s_waitcnt vmcnt(1)
	v_and_b32_e32 v139, 0xffff0000, v122
	v_mul_f32_e32 v130, v111, v111
	v_mul_f32_e32 v132, v109, v109
	v_lshlrev_b32_e32 v128, 16, v114
	v_and_b32_e32 v129, 0xffff0000, v114
	v_lshlrev_b32_e32 v114, 16, v115
	v_and_b32_e32 v115, 0xffff0000, v115
	v_lshlrev_b32_e32 v138, 16, v122
	v_pk_mul_f32 v[144:145], v[112:113], v[112:113]
	v_mov_b32_e32 v147, v131
	v_mul_f32_e32 v146, v139, v139
	v_pk_fma_f32 v[154:155], v[110:111], v[110:111], v[130:131] op_sel_hi:[1,1,0]
	v_pk_fma_f32 v[156:157], v[108:109], v[108:109], v[132:133] op_sel_hi:[1,1,0]
	v_lshlrev_b32_e32 v116, 16, v117
	v_and_b32_e32 v117, 0xffff0000, v117
	s_waitcnt vmcnt(0)
	v_lshlrev_b32_e32 v141, 16, v124
	v_and_b32_e32 v143, 0xffff0000, v124
	v_mul_f32_e32 v140, v129, v129
	v_mul_f32_e32 v142, v115, v115
	v_pk_fma_f32 v[144:145], v[126:127], v[126:127], v[144:145]
	v_pk_fma_f32 v[162:163], v[138:139], v[138:139], v[146:147] op_sel_hi:[1,1,0]
	v_mov_b32_e32 v130, v156
	v_mov_b32_e32 v146, v154
	v_mul_f32_e32 v91, v133, v133
	v_mul_f32_e32 v93, v116, v116
	v_mul_f32_e32 v95, v117, v117
	v_pk_fma_f32 v[158:159], v[128:129], v[128:129], v[140:141] op_sel_hi:[1,1,0]
	v_pk_fma_f32 v[160:161], v[114:115], v[114:115], v[142:143] op_sel_hi:[1,1,0]
	v_pk_add_f32 v[154:155], v[156:157], v[154:155]
	v_pk_add_f32 v[144:145], v[144:145], v[144:145] op_sel:[0,1] op_sel_hi:[1,0]
	v_pk_mul_f32 v[146:147], v[130:131], v[146:147]
	v_lshlrev_b32_e32 v135, 16, v119
	v_lshlrev_b32_e32 v134, 16, v118
	v_and_b32_e32 v119, 0xffff0000, v119
	v_and_b32_e32 v118, 0xffff0000, v118
	v_mov_b32_e32 v159, v93
	v_mov_b32_e32 v161, v95
	v_mov_b32_e32 v145, v91
	v_mov_b32_e32 v155, v147
	v_pk_mul_f32 v[148:149], v[118:119], v[118:119]
	v_pk_add_f32 v[156:157], v[158:159], v[160:161]
	v_pk_add_f32 v[144:145], v[154:155], v[144:145]
	v_lshlrev_b32_e32 v137, 16, v121
	v_lshlrev_b32_e32 v136, 16, v120
	v_and_b32_e32 v121, 0xffff0000, v121
	v_and_b32_e32 v120, 0xffff0000, v120
	v_lshlrev_b32_e32 v122, 16, v123
	v_and_b32_e32 v123, 0xffff0000, v123
	v_pk_fma_f32 v[148:149], v[134:135], v[134:135], v[148:149]
	v_pk_add_f32 v[144:145], v[144:145], v[156:157]
	v_pk_mul_f32 v[150:151], v[120:121], v[120:121]
	v_mov_b32_e32 v153, v141
	v_mul_f32_e32 v152, v123, v123
	v_pk_add_f32 v[148:149], v[148:149], v[148:149] op_sel:[0,1] op_sel_hi:[1,0]
	v_pk_add_f32 v[144:145], v[144:145], v[144:145] op_sel:[0,1] op_sel_hi:[1,0]
	v_lshlrev_b32_e32 v124, 16, v125
	v_and_b32_e32 v125, 0xffff0000, v125
	v_pk_fma_f32 v[150:151], v[136:137], v[136:137], v[150:151]
	v_pk_fma_f32 v[164:165], v[122:123], v[122:123], v[152:153] op_sel_hi:[1,1,0]
	v_mov_b32_e32 v152, v148
	v_mov_b32_e32 v140, v144
	v_mul_f32_e32 v97, v143, v143
	v_mul_f32_e32 v99, v124, v124
	v_mul_f32_e32 v107, v125, v125
	v_pk_add_f32 v[150:151], v[150:151], v[150:151] op_sel:[0,1] op_sel_hi:[1,0]
	v_pk_add_f32 v[144:145], v[144:145], v[148:149]
	v_pk_mul_f32 v[146:147], v[140:141], v[152:153]
	v_mov_b32_e32 v163, v99
	v_mov_b32_e32 v165, v107
	v_mov_b32_e32 v151, v97
	v_mov_b32_e32 v145, v147
	v_xor_b32_e32 v93, 1, v106
	v_pk_add_f32 v[158:159], v[162:163], v[164:165]
	v_pk_add_f32 v[144:145], v[144:145], v[150:151]
	v_cmp_lt_i32_e32 vcc, v93, v89
	v_pk_add_f32 v[144:145], v[144:145], v[158:159]
	v_mov_b32_e32 v132, v131
	v_cndmask_b32_e32 v93, v106, v93, vcc
	v_add_f32_e32 v91, v144, v145
	v_lshlrev_b32_e32 v93, 2, v93
	v_mov_b32_e32 v142, v141
	s_nop 0
	v_add_f32_dpp v91, v91, v91 quad_perm:[1,0,3,2] row_mask:0xf bank_mask:0xf
	s_nop 1
	v_add_f32_dpp v91, v91, v91 quad_perm:[2,3,0,1] row_mask:0xf bank_mask:0xf
	s_nop 1
	v_add_f32_dpp v91, v91, v91 row_half_mirror row_mask:0xf bank_mask:0xf
	s_nop 1
	v_add_f32_dpp v91, v91, v91 row_mirror row_mask:0xf bank_mask:0xf
	v_xor_b32_e32 v93, 16, v106
	v_cmp_lt_i32_e32 vcc, v93, v89
	s_nop 1
	v_cndmask_b32_e32 v93, v106, v93, vcc
	v_lshlrev_b32_e32 v93, 2, v93
	ds_bpermute_b32 v93, v93, v91
	s_waitcnt lgkmcnt(0)
; __device__ __forceinline__ unsigned cvt_pk_bf16(float lo, float hi) { const f32x2 v = {lo, hi}; const bf16v2_t b = __builtin_convertvector(v, bf16v2_t); return __builtin_bit_cast(unsigned, b); }
; __device__ __forceinline__ void norm_phase(const float* src_lat, const float* src_ctx, int nrows, const float* gain, const float* mod_l, int sh_chunk, int sc_chunk, bf16_t* dst, const bf16_t* lr_t = nullptr, bf16_t* lr_out = nullptr, const bf16_t* src16 = nullptr, LAS unsigned char* lds = nullptr) {
;     ...
;         const float rstd = rsqrtf(wave_sum(ss) * (1.f / D) + 1e-6f);
; #pragma unroll
;         for (int j = 0; j < 8; ++j) { const int c0 = (lane + 64 * j) * 4;
;             const f32x4 y = v[j] * rstd * gam[j] + shv[j];
;             u32x2 w; w.x = cvt_pk_bf16(y[0], y[1]); w.y = cvt_pk_bf16(y[2], y[3]);
;             *(u32x2*)(dst + (size_t)row * D + c0) = w; v[j] = y; }
	v_add_f32_e32 v91, v91, v93
	v_xor_b32_e32 v93, 32, v106
	v_cmp_lt_i32_e32 vcc, v93, v89
	s_nop 1
	v_cndmask_b32_e32 v89, v106, v93, vcc
	v_lshlrev_b32_e32 v89, 2, v89
	ds_bpermute_b32 v89, v89, v91
	s_waitcnt lgkmcnt(0)
	v_add_f32_e32 v89, v91, v89
	v_fmamk_f32 v89, v89, 0x3a000000, v105
	v_mul_f32_e32 v91, 0x4b800000, v89
	v_cmp_gt_f32_e32 vcc, s18, v89
	s_nop 1
	v_cndmask_b32_e32 v89, v89, v91, vcc
	v_rsq_f32_e32 v89, v89
	s_nop 0
	v_mul_f32_e32 v91, 0x45800000, v89
	v_cndmask_b32_e32 v130, v89, v91, vcc
	v_pk_mul_f32 v[108:109], v[130:131], v[108:109] op_sel_hi:[0,1]
	v_pk_mul_f32 v[110:111], v[130:131], v[110:111] op_sel_hi:[0,1]
	v_pk_fma_f32 v[110:111], v[34:35], v[110:111], v[2:3]
	v_pk_fma_f32 v[108:109], v[32:33], v[108:109], v[0:1]
	s_nop 0
	v_cvt_pk_bf16_f32 v108, v108, v109
	v_cvt_pk_bf16_f32 v109, v110, v111
	global_store_dwordx2 v[100:101], v[108:109], off
	v_mov_b32_e32 v108, v126
	v_mov_b32_e32 v109, v112
	v_mov_b32_e32 v112, v127
	v_pk_mul_f32 v[108:109], v[130:131], v[108:109] op_sel_hi:[0,1]
	v_pk_mul_f32 v[110:111], v[130:131], v[112:113] op_sel_hi:[0,1]
	v_pk_fma_f32 v[110:111], v[38:39], v[110:111], v[6:7]
	v_pk_fma_f32 v[108:109], v[36:37], v[108:109], v[4:5]
	s_nop 0
	v_cvt_pk_bf16_f32 v108, v108, v109
	v_cvt_pk_bf16_f32 v109, v110, v111
	global_store_dwordx2 v[100:101], v[108:109], off offset:512
	v_pk_mul_f32 v[108:109], v[130:131], v[128:129] op_sel_hi:[0,1]
	v_pk_mul_f32 v[110:111], v[130:131], v[114:115] op_sel_hi:[0,1]
	v_pk_fma_f32 v[110:111], v[42:43], v[110:111], v[10:11]
	v_pk_fma_f32 v[108:109], v[40:41], v[108:109], v[8:9]
	s_nop 0
	v_cvt_pk_bf16_f32 v108, v108, v109
	v_cvt_pk_bf16_f32 v109, v110, v111
	global_store_dwordx2 v[100:101], v[108:109], off offset:1024
	v_pk_mul_f32 v[108:109], v[130:131], v[132:133] op_sel_hi:[0,1]
	v_pk_mul_f32 v[110:111], v[130:131], v[116:117] op_sel_hi:[0,1]
	v_pk_fma_f32 v[110:111], v[46:47], v[110:111], v[14:15]
	v_pk_fma_f32 v[108:109], v[44:45], v[108:109], v[12:13]
	s_nop 0
	v_cvt_pk_bf16_f32 v108, v108, v109
	v_cvt_pk_bf16_f32 v109, v110, v111
	global_store_dwordx2 v[100:101], v[108:109], off offset:1536
	v_mov_b32_e32 v108, v134
	v_mov_b32_e32 v109, v118
	v_mov_b32_e32 v118, v135
	v_pk_mul_f32 v[108:109], v[130:131], v[108:109] op_sel_hi:[0,1]
	v_pk_mul_f32 v[110:111], v[130:131], v[118:119] op_sel_hi:[0,1]
	v_pk_fma_f32 v[110:111], v[50:51], v[110:111], v[18:19]
	v_pk_fma_f32 v[108:109], v[48:49], v[108:109], v[16:17]
	s_nop 0
	v_cvt_pk_bf16_f32 v108, v108, v109
	v_cvt_pk_bf16_f32 v109, v110, v111
	global_store_dwordx2 v[100:101], v[108:109], off offset:2048
	v_mov_b32_e32 v108, v136
	v_mov_b32_e32 v109, v120
	v_mov_b32_e32 v120, v137
	v_pk_mul_f32 v[108:109], v[130:131], v[108:109] op_sel_hi:[0,1]
	v_pk_mul_f32 v[110:111], v[130:131], v[120:121] op_sel_hi:[0,1]
	v_pk_fma_f32 v[110:111], v[54:55], v[110:111], v[22:23]
	v_pk_fma_f32 v[108:109], v[52:53], v[108:109], v[20:21]
	s_nop 0
	v_cvt_pk_bf16_f32 v108, v108, v109
	v_cvt_pk_bf16_f32 v109, v110, v111
	global_store_dwordx2 v[100:101], v[108:109], off offset:2560
	v_pk_mul_f32 v[108:109], v[130:131], v[138:139] op_sel_hi:[0,1]
	v_pk_mul_f32 v[110:111], v[130:131], v[122:123] op_sel_hi:[0,1]
	v_pk_fma_f32 v[110:111], v[58:59], v[110:111], v[26:27]
	v_pk_fma_f32 v[108:109], v[56:57], v[108:109], v[24:25]
	s_nop 0
	v_cvt_pk_bf16_f32 v108, v108, v109
	v_cvt_pk_bf16_f32 v109, v110, v111
	global_store_dwordx2 v[100:101], v[108:109], off offset:3072
	v_pk_mul_f32 v[108:109], v[130:131], v[142:143] op_sel_hi:[0,1]
	v_pk_mul_f32 v[110:111], v[130:131], v[124:125] op_sel_hi:[0,1]
	v_pk_fma_f32 v[110:111], v[62:63], v[110:111], v[30:31]
	v_pk_fma_f32 v[108:109], v[60:61], v[108:109], v[28:29]
	s_nop 0
	v_cvt_pk_bf16_f32 v108, v108, v109
	v_cvt_pk_bf16_f32 v109, v110, v111
	global_store_dwordx2 v[100:101], v[108:109], off offset:3584
